# ctx ln_rows phases: all global loads of a row issued up front (was ~28 serial round trips per row)
# baseline (speedup 1.0000x reference)
.LBB0_634:
	v_lshl_add_u64 v[32:33], s[10:11], 0, v[20:21]
	v_add_co_u32_e32 v76, vcc, 0x12a00000, v32
	s_nop 1
	v_addc_co_u32_e32 v77, vcc, 0, v33, vcc
	v_add_co_u32_e32 v78, vcc, 0x13200000, v32
	s_nop 1
	v_addc_co_u32_e32 v79, vcc, 0, v33, vcc
	v_add_co_u32_e32 v80, vcc, 0x13a00000, v32
	s_nop 1
	v_addc_co_u32_e32 v81, vcc, 0, v33, vcc
	v_add_co_u32_e32 v82, vcc, 0x14200000, v32
	s_nop 1
	v_addc_co_u32_e32 v83, vcc, 0, v33, vcc
	v_lshl_add_u64 v[84:85], s[10:11], 0, v[18:19]
	v_add_co_u32_e32 v84, vcc, 0x7200000, v84
	s_nop 1
	v_addc_co_u32_e32 v85, vcc, 0, v85, vcc
	global_load_dwordx4 v[86:89], v[76:77], off
	global_load_dwordx4 v[90:93], v[78:79], off
	global_load_dwordx4 v[94:97], v[80:81], off
	global_load_dwordx4 v[98:101], v[82:83], off
	global_load_dwordx2 v[102:103], v[84:85], off
	global_load_dwordx4 v[104:107], v[6:7], off
	global_load_dwordx4 v[108:111], v[76:77], off offset:1024
	global_load_dwordx4 v[112:115], v[78:79], off offset:1024
	global_load_dwordx4 v[116:119], v[80:81], off offset:1024
	global_load_dwordx4 v[120:123], v[82:83], off offset:1024
	global_load_dwordx2 v[124:125], v[84:85], off offset:512
	global_load_dwordx4 v[126:129], v[6:7], off offset:1024
	global_load_dwordx4 v[130:133], v[76:77], off offset:2048
	global_load_dwordx4 v[134:137], v[78:79], off offset:2048
	global_load_dwordx4 v[138:141], v[80:81], off offset:2048
	global_load_dwordx4 v[142:145], v[82:83], off offset:2048
	global_load_dwordx2 v[146:147], v[84:85], off offset:1024
	global_load_dwordx4 v[148:151], v[6:7], off offset:2048
	global_load_dwordx4 v[152:155], v[76:77], off offset:3072
	global_load_dwordx4 v[156:159], v[78:79], off offset:3072
	global_load_dwordx4 v[160:163], v[80:81], off offset:3072
	global_load_dwordx4 v[164:167], v[82:83], off offset:3072
	global_load_dwordx2 v[168:169], v[84:85], off offset:1536
	global_load_dwordx4 v[170:173], v[6:7], off offset:3072
	s_waitcnt vmcnt(0)
	s_nop 1
	s_nop 0
	v_pk_add_f32 v[34:35], v[88:89], v[92:93]
	v_pk_add_f32 v[36:37], v[86:87], v[90:91]
	s_nop 0
	v_pk_add_f32 v[22:23], v[94:95], v[98:99]
	v_pk_add_f32 v[24:25], v[96:97], v[100:101]
	v_pk_add_f32 v[28:29], v[36:37], v[22:23]
	v_pk_add_f32 v[26:27], v[34:35], v[24:25]
	s_nop 0
	v_cvt_f32_f16_e32 v34, v102
	v_cvt_f32_f16_sdwa v35, v102 dst_sel:DWORD dst_unused:UNUSED_PAD src0_sel:WORD_1
	v_cvt_f32_f16_e32 v32, v103
	v_cvt_f32_f16_sdwa v33, v103 dst_sel:DWORD dst_unused:UNUSED_PAD src0_sel:WORD_1
	v_pk_mul_f32 v[24:25], v[106:107], 0.5 op_sel_hi:[1, 0]
	v_pk_mul_f32 v[22:23], v[104:105], 0.5 op_sel_hi:[1, 0]
	v_pk_mul_f32 v[24:25], v[26:27], v[24:25]
	v_pk_mul_f32 v[22:23], v[28:29], v[22:23]
	v_pk_fma_f32 v[32:33], v[32:33], s[90:91], v[24:25] op_sel_hi:[1, 0, 1]
	v_pk_fma_f32 v[34:35], v[34:35], s[90:91], v[22:23] op_sel_hi:[1, 0, 1]
	v_mov_b32_e32 v25, v33
	v_pk_mov_b32 v[22:23], v[34:35], v[32:33] op_sel:[1, 0]
	v_mov_b32_e32 v24, v34
	v_pk_add_f32 v[22:23], v[22:23], v[24:25]
	s_nop 0
	v_add_f32_e32 v22, v22, v23
	v_add_f32_e32 v36, 0, v22
	v_pk_add_f32 v[38:39], v[110:111], v[114:115]
	v_pk_add_f32 v[44:45], v[108:109], v[112:113]
	v_pk_add_f32 v[22:23], v[116:117], v[120:121]
	v_pk_add_f32 v[24:25], v[118:119], v[122:123]
	v_pk_add_f32 v[28:29], v[44:45], v[22:23]
	v_pk_add_f32 v[26:27], v[38:39], v[24:25]
	v_cvt_f32_f16_e32 v38, v124
	v_cvt_f32_f16_sdwa v39, v124 dst_sel:DWORD dst_unused:UNUSED_PAD src0_sel:WORD_1
	v_cvt_f32_f16_e32 v44, v125
	v_cvt_f32_f16_sdwa v45, v125 dst_sel:DWORD dst_unused:UNUSED_PAD src0_sel:WORD_1
	v_pk_mul_f32 v[24:25], v[128:129], 0.5 op_sel_hi:[1, 0]
	v_pk_mul_f32 v[22:23], v[126:127], 0.5 op_sel_hi:[1, 0]
	v_pk_mul_f32 v[24:25], v[26:27], v[24:25]
	v_pk_mul_f32 v[26:27], v[28:29], v[22:23]
	v_pk_fma_f32 v[22:23], v[44:45], s[90:91], v[24:25] op_sel_hi:[1, 0, 1]
	v_pk_fma_f32 v[28:29], v[38:39], s[90:91], v[26:27] op_sel_hi:[1, 0, 1]
	v_mov_b32_e32 v27, v23
	v_pk_mov_b32 v[24:25], v[28:29], v[22:23] op_sel:[1, 0]
	v_mov_b32_e32 v26, v28
	v_pk_add_f32 v[24:25], v[24:25], v[26:27]
	s_nop 0
	v_pk_add_f32 v[38:39], v[24:25], v[24:25] op_sel:[0, 1] op_sel_hi:[1, 0]
	v_pk_add_f32 v[48:49], v[132:133], v[136:137]
	v_pk_add_f32 v[56:57], v[130:131], v[134:135]
	v_pk_add_f32 v[24:25], v[138:139], v[142:143]
	v_pk_add_f32 v[26:27], v[140:141], v[144:145]
	v_pk_add_f32 v[46:47], v[56:57], v[24:25]
	v_pk_add_f32 v[44:45], v[48:49], v[26:27]
	v_cvt_f32_f16_e32 v48, v146
	v_cvt_f32_f16_sdwa v49, v146 dst_sel:DWORD dst_unused:UNUSED_PAD src0_sel:WORD_1
	v_cvt_f32_f16_e32 v56, v147
	v_cvt_f32_f16_sdwa v57, v147 dst_sel:DWORD dst_unused:UNUSED_PAD src0_sel:WORD_1
	v_pk_mul_f32 v[26:27], v[150:151], 0.5 op_sel_hi:[1, 0]
	v_pk_mul_f32 v[24:25], v[148:149], 0.5 op_sel_hi:[1, 0]
	v_pk_mul_f32 v[26:27], v[44:45], v[26:27]
	v_pk_mul_f32 v[44:45], v[46:47], v[24:25]
	v_pk_fma_f32 v[24:25], v[56:57], s[90:91], v[26:27] op_sel_hi:[1, 0, 1]
	s_nop 0
	v_pk_fma_f32 v[26:27], v[48:49], s[90:91], v[44:45] op_sel_hi:[1, 0, 1]
	v_add_f32_e32 v46, v24, v25
	v_add_f32_e32 v44, v26, v27
	v_pk_add_f32 v[48:49], v[154:155], v[158:159]
	v_pk_add_f32 v[60:61], v[152:153], v[156:157]
	v_pk_add_f32 v[2:3], v[160:161], v[164:165]
	s_nop 0
	v_pk_add_f32 v[42:43], v[60:61], v[2:3]
	v_pk_add_f32 v[4:5], v[162:163], v[166:167]
	v_cvt_f32_f16_e32 v40, v168
	v_pk_add_f32 v[30:31], v[48:49], v[4:5]
	v_cvt_f32_f16_sdwa v41, v168 dst_sel:DWORD dst_unused:UNUSED_PAD src0_sel:WORD_1
	v_cvt_f32_f16_e32 v48, v169
	v_cvt_f32_f16_sdwa v49, v169 dst_sel:DWORD dst_unused:UNUSED_PAD src0_sel:WORD_1
	v_pk_mul_f32 v[4:5], v[172:173], 0.5 op_sel_hi:[1, 0]
	v_pk_mul_f32 v[2:3], v[170:171], 0.5 op_sel_hi:[1, 0]
	v_pk_mul_f32 v[4:5], v[30:31], v[4:5]
	v_pk_mul_f32 v[30:31], v[42:43], v[2:3]
	v_pk_fma_f32 v[2:3], v[48:49], s[90:91], v[4:5] op_sel_hi:[1, 0, 1]
	v_pk_fma_f32 v[30:31], v[40:41], s[90:91], v[30:31] op_sel_hi:[1, 0, 1]
	v_mov_b32_e32 v45, v2
	v_mov_b32_e32 v37, v30
	v_mov_b32_e32 v39, v31
	v_mov_b32_e32 v47, v3
	v_pk_add_f32 v[4:5], v[36:37], v[38:39]
	v_pk_add_f32 v[36:37], v[44:45], v[46:47]
	s_nop 0
	v_pk_add_f32 v[4:5], v[4:5], v[36:37]
	s_nop 0
	v_add_f32_e32 v4, v4, v5
	v_mov_b32_e32 v56, v164
	v_mov_b32_e32 v57, v165
	v_mov_b32_e32 v58, v166
	v_mov_b32_e32 v59, v167
	ds_bpermute_b32 v5, v0, v4
	s_waitcnt lgkmcnt(0)
	v_add_f32_e32 v4, v4, v5
	ds_bpermute_b32 v5, v50, v4
	s_waitcnt lgkmcnt(0)
	v_add_f32_e32 v4, v4, v5
	ds_bpermute_b32 v5, v51, v4
	s_waitcnt lgkmcnt(0)
	v_add_f32_e32 v4, v4, v5
	ds_bpermute_b32 v5, v52, v4
	s_waitcnt lgkmcnt(0)
	v_add_f32_e32 v4, v4, v5
	ds_bpermute_b32 v5, v53, v4
	s_waitcnt lgkmcnt(0)
	v_add_f32_e32 v4, v4, v5
	ds_bpermute_b32 v5, v54, v4
	s_waitcnt lgkmcnt(0)
	v_add_f32_e32 v42, v4, v5
	v_fmamk_f32 v35, v42, 0xba800000, v35
	v_fmac_f32_e32 v34, 0xba800000, v42
	v_fmamk_f32 v33, v42, 0xba800000, v33
	v_fmac_f32_e32 v32, 0xba800000, v42
	v_pk_mul_f32 v[4:5], v[32:33], v[32:33]
	v_pk_mul_f32 v[36:37], v[34:35], v[34:35]
	v_fmamk_f32 v23, v42, 0xba800000, v23
	v_pk_mov_b32 v[38:39], v[36:37], v[4:5] op_sel:[1,0]
	v_mov_b32_e32 v37, v5
	v_pk_add_f32 v[4:5], v[38:39], v[36:37]
	v_fmac_f32_e32 v22, 0xba800000, v42
	v_fmamk_f32 v29, v42, 0xba800000, v29
	v_fmac_f32_e32 v28, 0xba800000, v42
	v_pk_add_f32 v[4:5], v[4:5], v[4:5] op_sel_hi:[0,1]
	v_pk_mul_f32 v[36:37], v[22:23], v[22:23]
	v_pk_mul_f32 v[38:39], v[28:29], v[28:29]
	v_fmac_f32_e32 v26, 0xba800000, v42
	v_pk_mov_b32 v[40:41], v[38:39], v[36:37] op_sel:[1,0]
	v_mov_b32_e32 v39, v37
	v_fmac_f32_e32 v24, 0xba800000, v42
	v_fmamk_f32 v27, v42, 0xba800000, v27
	v_mul_f32_e32 v4, v26, v26
	v_pk_add_f32 v[36:37], v[40:41], v[38:39]
	v_fmamk_f32 v25, v42, 0xba800000, v25
	v_pk_fma_f32 v[38:39], v[26:27], v[26:27], v[4:5] op_sel_hi:[1,1,0]
	v_mul_f32_e32 v4, v24, v24
	v_pk_add_f32 v[36:37], v[36:37], v[36:37] op_sel_hi:[0,1]
	v_pk_fma_f32 v[40:41], v[24:25], v[24:25], v[4:5] op_sel_hi:[1,1,0]
	v_fmamk_f32 v3, v42, 0xba800000, v3
	v_fmac_f32_e32 v2, 0xba800000, v42
	v_fmamk_f32 v31, v42, 0xba800000, v31
	v_fmac_f32_e32 v30, 0xba800000, v42
	v_mul_f32_e32 v38, v30, v30
	v_mul_f32_e32 v40, v31, v31
	v_mul_f32_e32 v4, v2, v2
	v_mul_f32_e32 v36, v3, v3
	v_pk_add_f32 v[38:39], v[38:39], v[40:41]
	v_pk_add_f32 v[4:5], v[4:5], v[36:37]
	s_nop 0
	v_pk_add_f32 v[4:5], v[38:39], v[4:5]
	s_nop 0
	v_add_f32_e32 v4, v4, v5
	ds_bpermute_b32 v5, v0, v4
	s_waitcnt lgkmcnt(0)
	v_add_f32_e32 v4, v4, v5
	ds_bpermute_b32 v5, v50, v4
	s_waitcnt lgkmcnt(0)
	v_add_f32_e32 v4, v4, v5
	ds_bpermute_b32 v5, v51, v4
	s_waitcnt lgkmcnt(0)
	v_add_f32_e32 v4, v4, v5
	ds_bpermute_b32 v5, v52, v4
	s_waitcnt lgkmcnt(0)
	v_add_f32_e32 v4, v4, v5
	ds_bpermute_b32 v5, v53, v4
	s_waitcnt lgkmcnt(0)
	v_add_f32_e32 v4, v4, v5
	ds_bpermute_b32 v5, v54, v4
	s_waitcnt lgkmcnt(0)
	v_add_f32_e32 v4, v4, v5
	v_fmamk_f32 v4, v4, 0x3a800000, v247
	v_cmp_gt_f32_e32 vcc, s96, v4
	v_mul_f32_e32 v5, 0x4f800000, v4
	s_nop 0
	v_cndmask_b32_e32 v4, v4, v5, vcc
	v_sqrt_f32_e32 v5, v4
	s_nop 0
	v_add_u32_e32 v36, -1, v5
	v_fma_f32 v37, -v36, v5, v4
	v_cmp_ge_f32_e64 s[6:7], 0, v37
	v_add_u32_e32 v37, 1, v5
	s_nop 0
	v_cndmask_b32_e64 v36, v5, v36, s[6:7]
	v_fma_f32 v5, -v37, v5, v4
	v_cmp_lt_f32_e64 s[6:7], 0, v5
	s_nop 1
	v_cndmask_b32_e64 v5, v36, v37, s[6:7]
	v_mul_f32_e32 v36, 0x37800000, v5
	v_cndmask_b32_e32 v5, v5, v36, vcc
	v_cmp_class_f32_e32 vcc, v4, v248
	s_nop 1
	v_cndmask_b32_e32 v4, v5, v4, vcc
	v_div_scale_f32 v5, s[6:7], v4, v4, 1.0
	v_rcp_f32_e32 v36, v5
	s_nop 0
	v_fma_f32 v37, -v5, v36, 1.0
	v_fmac_f32_e32 v36, v37, v36
	v_div_scale_f32 v37, vcc, 1.0, v4, 1.0
	v_mul_f32_e32 v38, v37, v36
	v_fma_f32 v39, -v5, v38, v37
	v_fmac_f32_e32 v38, v39, v36
	v_fma_f32 v5, -v5, v38, v37
	v_div_fmas_f32 v5, v5, v36, v38
	global_load_dwordx4 v[38:41], v[8:9], off
	global_load_dwordx4 v[42:45], v[10:11], off
	v_div_fixup_f32 v4, v5, v4, 1.0
	v_mov_b32_e32 v5, v4
	v_pk_mul_f32 v[32:33], v[32:33], v[4:5] op_sel_hi:[1,0]
	v_pk_mul_f32 v[34:35], v[34:35], v[4:5] op_sel_hi:[1,0]
	v_pk_mul_f32 v[28:29], v[28:29], v[4:5]
	s_waitcnt vmcnt(0)
	v_pk_fma_f32 v[36:37], v[40:41], v[32:33], v[44:45]
	v_lshl_add_u64 v[32:33], s[10:11], 0, v[16:17]
	v_pk_fma_f32 v[34:35], v[38:39], v[34:35], v[42:43]
	v_add_co_u32_e32 v40, vcc, 0x5200000, v32
	v_cvt_pk_f16_f32 v39, v36, v37
	v_cvt_pk_f16_f32 v38, v34, v35
	v_addc_co_u32_e32 v41, vcc, 0, v33, vcc
	global_store_dwordx2 v[40:41], v[38:39], off
	v_cndmask_b32_e64 v38, 0, 1, s[14:15]
	v_cmp_ne_u32_e64 s[6:7], 1, v38
	s_andn2_b64 vcc, exec, s[14:15]
	s_cbranch_vccnz .LBB0_639
	global_load_dwordx4 v[76:79], v[12:13], off
	global_load_dwordx4 v[80:83], v[14:15], off
	global_load_dwordx4 v[84:87], v[8:9], off offset:1024
	global_load_dwordx4 v[88:91], v[10:11], off offset:1024
	global_load_dwordx4 v[92:95], v[12:13], off offset:1024
	global_load_dwordx4 v[96:99], v[14:15], off offset:1024
	s_waitcnt vmcnt(0)
	v_pk_add_f32 v[42:43], v[78:79], 1.0 op_sel_hi:[1, 0]
	v_pk_add_f32 v[44:45], v[76:77], 1.0 op_sel_hi:[1, 0]
	v_pk_fma_f32 v[36:37], v[36:37], v[42:43], v[82:83]
	v_pk_fma_f32 v[34:35], v[34:35], v[44:45], v[80:81]
	v_add_co_u32_e32 v42, vcc, s5, v32
	v_cvt_pk_bf16_f32 v34, v34, v35
	v_cvt_pk_bf16_f32 v35, v36, v37
	s_nop 1
	v_addc_co_u32_e32 v43, vcc, 0, v33, vcc
	global_store_dwordx2 v[42:43], v[34:35], off
	v_mov_b32_e32 v34, v4
	v_mov_b32_e32 v35, v4
	v_pk_mul_f32 v[44:45], v[22:23], v[34:35]
	v_pk_fma_f32 v[40:41], v[44:45], v[86:87], v[90:91]
	v_pk_fma_f32 v[38:39], v[28:29], v[84:85], v[88:89]
	v_add_co_u32_e32 v36, vcc, s2, v32
	v_cvt_pk_f16_f32 v35, v40, v41
	v_cvt_pk_f16_f32 v34, v38, v39
	v_addc_co_u32_e32 v37, vcc, 0, v33, vcc
	global_store_dwordx2 v[36:37], v[34:35], off offset:512
	v_pk_add_f32 v[44:45], v[94:95], 1.0 op_sel_hi:[1, 0]
	v_pk_add_f32 v[46:47], v[92:93], 1.0 op_sel_hi:[1, 0]
	v_pk_fma_f32 v[34:35], v[38:39], v[46:47], v[96:97]
	v_pk_fma_f32 v[36:37], v[40:41], v[44:45], v[98:99]
	v_cvt_pk_bf16_f32 v34, v34, v35
	s_nop 0
	v_cvt_pk_bf16_f32 v35, v36, v37
	global_store_dwordx2 v[42:43], v[34:35], off offset:512
	s_cbranch_execnz .LBB0_637

.LBB0_637:
	global_load_dwordx4 v[34:37], v[8:9], off offset:2048
	global_load_dwordx4 v[38:41], v[10:11], off offset:2048
	v_mov_b32_e32 v28, v4
	v_mov_b32_e32 v29, v4
	v_pk_mul_f32 v[22:23], v[26:27], v[4:5]
	v_add_co_u32_e32 v42, vcc, 0x5200000, v32
	v_pk_mul_f32 v[24:25], v[24:25], v[28:29]
	s_mov_b64 s[8:9], vcc
	s_and_b64 vcc, exec, s[6:7]
	v_addc_co_u32_e64 v43, s[6:7], 0, v33, s[8:9]
	s_waitcnt vmcnt(0)
	v_pk_fma_f32 v[24:25], v[24:25], v[36:37], v[40:41]
	v_pk_fma_f32 v[26:27], v[22:23], v[34:35], v[38:39]
	v_cvt_pk_f16_f32 v23, v24, v25
	v_cvt_pk_f16_f32 v22, v26, v27
	global_store_dwordx2 v[42:43], v[22:23], off offset:1024
	v_pk_mul_f32 v[22:23], v[30:31], v[4:5]
	s_cbranch_vccnz .LBB0_640
	global_load_dwordx4 v[76:79], v[12:13], off offset:2048
	global_load_dwordx4 v[80:83], v[14:15], off offset:2048
	global_load_dwordx4 v[84:87], v[8:9], off offset:3072
	global_load_dwordx4 v[88:91], v[10:11], off offset:3072
	global_load_dwordx4 v[92:95], v[12:13], off offset:3072
	global_load_dwordx4 v[96:99], v[14:15], off offset:3072
	s_waitcnt vmcnt(0)
	v_pk_add_f32 v[30:31], v[78:79], 1.0 op_sel_hi:[1, 0]
	v_pk_add_f32 v[38:39], v[76:77], 1.0 op_sel_hi:[1, 0]
	v_pk_fma_f32 v[26:27], v[26:27], v[38:39], v[80:81]
	v_add_co_u32_e32 v34, vcc, s5, v32
	v_pk_fma_f32 v[24:25], v[24:25], v[30:31], v[82:83]
	s_nop 0
	v_addc_co_u32_e32 v35, vcc, 0, v33, vcc
	v_cvt_pk_bf16_f32 v26, v26, v27
	v_cvt_pk_bf16_f32 v27, v24, v25
	global_store_dwordx2 v[34:35], v[26:27], off offset:1024
	v_pk_mul_f32 v[36:37], v[2:3], v[28:29]
	v_pk_fma_f32 v[30:31], v[36:37], v[86:87], v[90:91]
	v_pk_fma_f32 v[28:29], v[22:23], v[84:85], v[88:89]
	v_add_co_u32_e32 v26, vcc, s2, v32
	v_cvt_pk_f16_f32 v25, v30, v31
	v_cvt_pk_f16_f32 v24, v28, v29
	v_addc_co_u32_e32 v27, vcc, 0, v33, vcc
	global_store_dwordx2 v[26:27], v[24:25], off offset:1536
	v_pk_add_f32 v[36:37], v[94:95], 1.0 op_sel_hi:[1, 0]
	v_pk_add_f32 v[38:39], v[92:93], 1.0 op_sel_hi:[1, 0]
	v_pk_fma_f32 v[24:25], v[28:29], v[38:39], v[96:97]
	v_pk_fma_f32 v[26:27], v[30:31], v[36:37], v[98:99]
	v_cvt_pk_bf16_f32 v24, v24, v25
	s_nop 0
	v_cvt_pk_bf16_f32 v25, v26, v27
	global_store_dwordx2 v[34:35], v[24:25], off offset:1536
	s_cbranch_execnz .LBB0_633
	s_branch .LBB0_641

.LBB0_1271:
	v_lshl_add_u64 v[48:49], s[6:7], 0, v[34:35]
	v_add_co_u32_e32 v76, vcc, 0x12a00000, v48
	s_nop 1
	v_addc_co_u32_e32 v77, vcc, 0, v49, vcc
	v_add_co_u32_e32 v78, vcc, 0x13200000, v48
	s_nop 1
	v_addc_co_u32_e32 v79, vcc, 0, v49, vcc
	v_add_co_u32_e32 v80, vcc, 0x13a00000, v48
	s_nop 1
	v_addc_co_u32_e32 v81, vcc, 0, v49, vcc
	v_add_co_u32_e32 v82, vcc, 0x14200000, v48
	s_nop 1
	v_addc_co_u32_e32 v83, vcc, 0, v49, vcc
	v_lshl_add_u64 v[84:85], s[6:7], 0, v[32:33]
	v_add_co_u32_e32 v84, vcc, 0x7200000, v84
	s_nop 1
	v_addc_co_u32_e32 v85, vcc, 0, v85, vcc
	global_load_dwordx4 v[86:89], v[76:77], off
	global_load_dwordx4 v[90:93], v[78:79], off
	global_load_dwordx4 v[94:97], v[80:81], off
	global_load_dwordx4 v[98:101], v[82:83], off
	global_load_dwordx2 v[102:103], v[84:85], off
	global_load_dwordx4 v[104:107], v[2:3], off
	global_load_dwordx4 v[108:111], v[76:77], off offset:1024
	global_load_dwordx4 v[112:115], v[78:79], off offset:1024
	global_load_dwordx4 v[116:119], v[80:81], off offset:1024
	global_load_dwordx4 v[120:123], v[82:83], off offset:1024
	global_load_dwordx2 v[124:125], v[84:85], off offset:512
	global_load_dwordx4 v[126:129], v[4:5], off
	global_load_dwordx4 v[130:133], v[76:77], off offset:2048
	global_load_dwordx4 v[134:137], v[78:79], off offset:2048
	global_load_dwordx4 v[138:141], v[80:81], off offset:2048
	global_load_dwordx4 v[142:145], v[82:83], off offset:2048
	global_load_dwordx2 v[146:147], v[84:85], off offset:1024
	global_load_dwordx4 v[148:151], v[6:7], off
	global_load_dwordx4 v[152:155], v[76:77], off offset:3072
	global_load_dwordx4 v[156:159], v[78:79], off offset:3072
	global_load_dwordx4 v[160:163], v[80:81], off offset:3072
	global_load_dwordx4 v[164:167], v[82:83], off offset:3072
	global_load_dwordx2 v[168:169], v[84:85], off offset:1536
	global_load_dwordx4 v[170:173], v[8:9], off
	s_waitcnt vmcnt(0)
	s_add_i32 s8, s8, s38
	s_nop 0
	s_nop 0
	v_lshl_add_u64 v[34:35], v[34:35], 0, s[22:23]
	s_nop 0
	s_cmpk_lt_i32 s8, 0x4800
	s_nop 0
	v_pk_add_f32 v[50:51], v[88:89], v[92:93]
	v_pk_add_f32 v[56:57], v[86:87], v[90:91]
	v_pk_add_f32 v[36:37], v[94:95], v[98:99]
	v_pk_add_f32 v[38:39], v[96:97], v[100:101]
	v_pk_add_f32 v[42:43], v[56:57], v[36:37]
	v_pk_add_f32 v[40:41], v[50:51], v[38:39]
	s_nop 0
	v_lshl_add_u64 v[32:33], v[32:33], 0, s[20:21]
	v_cvt_f32_f16_e32 v48, v102
	v_cvt_f32_f16_sdwa v49, v102 dst_sel:DWORD dst_unused:UNUSED_PAD src0_sel:WORD_1
	v_cvt_f32_f16_e32 v50, v103
	v_cvt_f32_f16_sdwa v51, v103 dst_sel:DWORD dst_unused:UNUSED_PAD src0_sel:WORD_1
	v_pk_mul_f32 v[38:39], v[40:41], v[106:107]
	v_pk_mul_f32 v[36:37], v[42:43], v[104:105]
	v_pk_fma_f32 v[50:51], v[50:51], s[90:91], v[38:39] op_sel_hi:[1, 0, 1]
	v_pk_fma_f32 v[48:49], v[48:49], s[90:91], v[36:37] op_sel_hi:[1, 0, 1]
	v_mov_b32_e32 v39, v51
	v_pk_mov_b32 v[36:37], v[48:49], v[50:51] op_sel:[1, 0]
	v_mov_b32_e32 v38, v48
	v_pk_add_f32 v[36:37], v[36:37], v[38:39]
	s_nop 0
	v_add_f32_e32 v0, v36, v37
	v_add_f32_e32 v56, 0, v0
	v_pk_add_f32 v[66:67], v[110:111], v[114:115]
	v_pk_add_f32 v[68:69], v[108:109], v[112:113]
	v_pk_add_f32 v[36:37], v[116:117], v[120:121]
	v_pk_add_f32 v[38:39], v[118:119], v[122:123]
	v_pk_add_f32 v[42:43], v[68:69], v[36:37]
	v_pk_add_f32 v[40:41], v[66:67], v[38:39]
	v_cvt_f32_f16_e32 v66, v124
	v_cvt_f32_f16_sdwa v67, v124 dst_sel:DWORD dst_unused:UNUSED_PAD src0_sel:WORD_1
	v_cvt_f32_f16_e32 v68, v125
	v_cvt_f32_f16_sdwa v69, v125 dst_sel:DWORD dst_unused:UNUSED_PAD src0_sel:WORD_1
	v_pk_mul_f32 v[38:39], v[40:41], v[128:129]
	v_pk_mul_f32 v[40:41], v[42:43], v[126:127]
	v_pk_fma_f32 v[36:37], v[68:69], s[90:91], v[38:39] op_sel_hi:[1, 0, 1]
	v_pk_fma_f32 v[38:39], v[66:67], s[90:91], v[40:41] op_sel_hi:[1, 0, 1]
	v_mov_b32_e32 v43, v37
	v_pk_mov_b32 v[40:41], v[38:39], v[36:37] op_sel:[1, 0]
	v_mov_b32_e32 v42, v38
	v_pk_add_f32 v[40:41], v[40:41], v[42:43]
	s_nop 0
	v_pk_add_f32 v[70:71], v[40:41], v[40:41] op_sel:[0, 1] op_sel_hi:[1, 0]
	v_pk_add_f32 v[72:73], v[132:133], v[136:137]
	v_pk_add_f32 v[74:75], v[130:131], v[134:135]
	v_pk_add_f32 v[40:41], v[138:139], v[142:143]
	v_pk_add_f32 v[42:43], v[140:141], v[144:145]
	v_pk_add_f32 v[68:69], v[74:75], v[40:41]
	v_pk_add_f32 v[66:67], v[72:73], v[42:43]
	v_cvt_f32_f16_e32 v72, v146
	v_cvt_f32_f16_sdwa v73, v146 dst_sel:DWORD dst_unused:UNUSED_PAD src0_sel:WORD_1
	v_cvt_f32_f16_e32 v74, v147
	v_cvt_f32_f16_sdwa v75, v147 dst_sel:DWORD dst_unused:UNUSED_PAD src0_sel:WORD_1
	v_pk_mul_f32 v[42:43], v[66:67], v[150:151]
	v_pk_mul_f32 v[66:67], v[68:69], v[148:149]
	v_pk_fma_f32 v[40:41], v[74:75], s[90:91], v[42:43] op_sel_hi:[1, 0, 1]
	v_pk_fma_f32 v[42:43], v[72:73], s[90:91], v[66:67] op_sel_hi:[1, 0, 1]
	s_nop 0
	v_add_f32_e32 v72, v42, v43
	v_add_f32_e32 v74, v40, v41
	v_pk_add_f32 v[68:69], v[154:155], v[158:159]
	v_pk_add_f32 v[66:67], v[152:153], v[156:157]
	s_nop 0
	v_pk_add_f32 v[44:45], v[160:161], v[164:165]
	v_pk_add_f32 v[46:47], v[162:163], v[166:167]
	v_pk_add_f32 v[54:55], v[66:67], v[44:45]
	v_pk_add_f32 v[52:53], v[68:69], v[46:47]
	v_cvt_f32_f16_e32 v58, v168
	v_cvt_f32_f16_sdwa v59, v168 dst_sel:DWORD dst_unused:UNUSED_PAD src0_sel:WORD_1
	v_cvt_f32_f16_e32 v66, v169
	v_cvt_f32_f16_sdwa v67, v169 dst_sel:DWORD dst_unused:UNUSED_PAD src0_sel:WORD_1
	v_pk_mul_f32 v[46:47], v[52:53], v[172:173]
	v_pk_mul_f32 v[52:53], v[54:55], v[170:171]
	v_pk_fma_f32 v[44:45], v[66:67], s[90:91], v[46:47] op_sel_hi:[1, 0, 1]
	v_pk_fma_f32 v[46:47], v[58:59], s[90:91], v[52:53] op_sel_hi:[1, 0, 1]
	v_mov_b32_e32 v73, v44
	v_mov_b32_e32 v57, v46
	v_mov_b32_e32 v71, v47
	v_mov_b32_e32 v75, v45
	v_pk_add_f32 v[52:53], v[56:57], v[70:71]
	v_pk_add_f32 v[54:55], v[72:73], v[74:75]
	s_nop 0
	v_pk_add_f32 v[52:53], v[52:53], v[54:55]
	s_nop 0
	v_add_f32_e32 v0, v52, v53
	ds_bpermute_b32 v52, v60, v0
	s_waitcnt lgkmcnt(0)
	v_add_f32_e32 v0, v0, v52
	ds_bpermute_b32 v52, v61, v0
	s_waitcnt lgkmcnt(0)
	v_add_f32_e32 v0, v0, v52
	ds_bpermute_b32 v52, v62, v0
	s_waitcnt lgkmcnt(0)
	v_add_f32_e32 v0, v0, v52
	ds_bpermute_b32 v52, v63, v0
	s_waitcnt lgkmcnt(0)
	v_add_f32_e32 v0, v0, v52
	ds_bpermute_b32 v52, v64, v0
	s_waitcnt lgkmcnt(0)
	v_add_f32_e32 v0, v0, v52
	ds_bpermute_b32 v52, v65, v0
	s_waitcnt lgkmcnt(0)
	v_add_f32_e32 v66, v0, v52
	v_fmamk_f32 v49, v66, 0xba800000, v49
	v_fmac_f32_e32 v48, 0xba800000, v66
	v_fmamk_f32 v51, v66, 0xba800000, v51
	v_fmac_f32_e32 v50, 0xba800000, v66
	v_pk_mul_f32 v[52:53], v[50:51], v[50:51]
	v_pk_mul_f32 v[54:55], v[48:49], v[48:49]
	v_fmamk_f32 v39, v66, 0xba800000, v39
	v_pk_mov_b32 v[56:57], v[54:55], v[52:53] op_sel:[1,0]
	v_mov_b32_e32 v55, v53
	v_fmac_f32_e32 v38, 0xba800000, v66
	v_fmamk_f32 v37, v66, 0xba800000, v37
	v_fmac_f32_e32 v36, 0xba800000, v66
	v_pk_add_f32 v[52:53], v[56:57], v[54:55]
	v_pk_mul_f32 v[54:55], v[36:37], v[36:37]
	v_pk_mul_f32 v[56:57], v[38:39], v[38:39]
	v_fmac_f32_e32 v42, 0xba800000, v66
	v_pk_mov_b32 v[58:59], v[56:57], v[54:55] op_sel:[1,0]
	v_mov_b32_e32 v57, v55
	v_fmamk_f32 v43, v66, 0xba800000, v43
	v_fmac_f32_e32 v40, 0xba800000, v66
	v_mul_f32_e32 v0, v42, v42
	v_pk_add_f32 v[54:55], v[58:59], v[56:57]
	v_fmamk_f32 v41, v66, 0xba800000, v41
	v_pk_fma_f32 v[56:57], v[42:43], v[42:43], v[0:1] op_sel_hi:[1,1,0]
	v_mul_f32_e32 v0, v40, v40
	v_pk_add_f32 v[52:53], v[52:53], v[52:53] op_sel_hi:[0,1]
	v_pk_add_f32 v[54:55], v[54:55], v[54:55] op_sel_hi:[0,1]
	v_pk_fma_f32 v[58:59], v[40:41], v[40:41], v[0:1] op_sel_hi:[1,1,0]
	v_fmamk_f32 v45, v66, 0xba800000, v45
	v_fmac_f32_e32 v44, 0xba800000, v66
	v_fmamk_f32 v47, v66, 0xba800000, v47
	v_fmac_f32_e32 v46, 0xba800000, v66
	v_mul_f32_e32 v56, v46, v46
	v_mul_f32_e32 v58, v47, v47
	v_mul_f32_e32 v52, v44, v44
	v_mul_f32_e32 v54, v45, v45
	v_pk_add_f32 v[56:57], v[56:57], v[58:59]
	v_pk_add_f32 v[52:53], v[52:53], v[54:55]
	s_nop 0
	v_pk_add_f32 v[52:53], v[56:57], v[52:53]
	s_nop 0
	v_add_f32_e32 v0, v52, v53
	ds_bpermute_b32 v52, v60, v0
	s_waitcnt lgkmcnt(0)
	v_add_f32_e32 v0, v0, v52
	ds_bpermute_b32 v52, v61, v0
	s_waitcnt lgkmcnt(0)
	v_add_f32_e32 v0, v0, v52
	ds_bpermute_b32 v52, v62, v0
	s_waitcnt lgkmcnt(0)
	v_add_f32_e32 v0, v0, v52
	ds_bpermute_b32 v52, v63, v0
	s_waitcnt lgkmcnt(0)
	v_add_f32_e32 v0, v0, v52
	ds_bpermute_b32 v52, v64, v0
	s_waitcnt lgkmcnt(0)
	v_add_f32_e32 v0, v0, v52
	ds_bpermute_b32 v52, v65, v0
	s_waitcnt lgkmcnt(0)
	v_add_f32_e32 v0, v0, v52
	global_load_dwordx4 v[76:79], v[10:11], off
	global_load_dwordx4 v[80:83], v[12:13], off
	global_load_dwordx4 v[84:87], v[14:15], off
	global_load_dwordx4 v[88:91], v[16:17], off
	global_load_dwordx4 v[92:95], v[10:11], off offset:1024
	global_load_dwordx4 v[96:99], v[12:13], off offset:1024
	global_load_dwordx4 v[100:103], v[18:19], off
	global_load_dwordx4 v[104:107], v[20:21], off
	global_load_dwordx4 v[108:111], v[10:11], off offset:2048
	global_load_dwordx4 v[112:115], v[12:13], off offset:2048
	global_load_dwordx4 v[116:119], v[22:23], off
	global_load_dwordx4 v[120:123], v[24:25], off
	global_load_dwordx4 v[124:127], v[10:11], off offset:3072
	global_load_dwordx4 v[128:131], v[12:13], off offset:3072
	global_load_dwordx4 v[132:135], v[26:27], off
	global_load_dwordx4 v[136:139], v[28:29], off
	s_waitcnt vmcnt(0)
	v_fmamk_f32 v0, v0, 0x3a800000, v247
	v_cmp_gt_f32_e32 vcc, s96, v0
	v_mul_f32_e32 v52, 0x4f800000, v0
	s_nop 0
	v_cndmask_b32_e32 v0, v0, v52, vcc
	v_sqrt_f32_e32 v52, v0
	s_nop 0
	v_add_u32_e32 v53, -1, v52
	v_fma_f32 v54, -v53, v52, v0
	v_cmp_ge_f32_e64 s[4:5], 0, v54
	v_add_u32_e32 v54, 1, v52
	s_nop 0
	v_cndmask_b32_e64 v53, v52, v53, s[4:5]
	v_fma_f32 v52, -v54, v52, v0
	v_cmp_lt_f32_e64 s[4:5], 0, v52
	s_nop 1
	v_cndmask_b32_e64 v52, v53, v54, s[4:5]
	v_mul_f32_e32 v53, 0x37800000, v52
	v_cndmask_b32_e32 v52, v52, v53, vcc
	v_cmp_class_f32_e32 vcc, v0, v248
	s_nop 1
	v_cndmask_b32_e32 v0, v52, v0, vcc
	v_div_scale_f32 v52, s[4:5], v0, v0, 1.0
	v_rcp_f32_e32 v53, v52
	s_nop 0
	v_fma_f32 v54, -v52, v53, 1.0
	v_fmac_f32_e32 v53, v54, v53
	v_div_scale_f32 v54, vcc, 1.0, v0, 1.0
	v_mul_f32_e32 v55, v54, v53
	v_fma_f32 v56, -v52, v55, v54
	v_fmac_f32_e32 v55, v56, v53
	v_fma_f32 v52, -v52, v55, v54
	v_div_fmas_f32 v52, v52, v53, v55
	v_div_fixup_f32 v0, v52, v0, 1.0
	v_pk_mul_f32 v[50:51], v[50:51], v[0:1] op_sel_hi:[1, 0]
	v_pk_mul_f32 v[48:49], v[48:49], v[0:1] op_sel_hi:[1, 0]
	v_pk_mul_f32 v[46:47], v[46:47], v[0:1] op_sel_hi:[1, 0]
	v_pk_mul_f32 v[44:45], v[44:45], v[0:1] op_sel_hi:[1, 0]
	v_pk_fma_f32 v[54:55], v[78:79], v[50:51], v[82:83]
	v_lshl_add_u64 v[50:51], s[6:7], 0, v[30:31]
	v_pk_fma_f32 v[52:53], v[76:77], v[48:49], v[80:81]
	v_add_co_u32_e32 v48, vcc, s18, v50
	v_cvt_pk_f16_f32 v57, v54, v55
	v_cvt_pk_f16_f32 v56, v52, v53
	v_addc_co_u32_e32 v49, vcc, 0, v51, vcc
	global_store_dwordx2 v[48:49], v[56:57], off
	v_lshl_add_u64 v[30:31], v[30:31], 0, s[20:21]
	v_pk_add_f32 v[66:67], v[86:87], 1.0 op_sel_hi:[1, 0]
	v_pk_add_f32 v[68:69], v[84:85], 1.0 op_sel_hi:[1, 0]
	v_pk_fma_f32 v[54:55], v[66:67], v[54:55], v[90:91]
	v_pk_fma_f32 v[52:53], v[68:69], v[52:53], v[88:89]
	v_pk_mul_f32 v[56:57], v[38:39], v[0:1] op_sel_hi:[1, 0]
	v_cvt_pk_bf16_f32 v52, v52, v53
	v_cvt_pk_bf16_f32 v53, v54, v55
	v_add_co_u32_e32 v54, vcc, s19, v50
	v_pk_mul_f32 v[58:59], v[36:37], v[0:1] op_sel_hi:[1, 0]
	s_nop 0
	v_addc_co_u32_e32 v55, vcc, 0, v51, vcc
	global_store_dwordx2 v[54:55], v[52:53], off
	s_nop 0
	v_pk_fma_f32 v[52:53], v[94:95], v[58:59], v[98:99]
	v_pk_fma_f32 v[50:51], v[92:93], v[56:57], v[96:97]
	v_cvt_pk_f16_f32 v37, v52, v53
	v_cvt_pk_f16_f32 v36, v50, v51
	global_store_dwordx2 v[48:49], v[36:37], off offset:512
	v_pk_add_f32 v[56:57], v[102:103], 1.0 op_sel_hi:[1, 0]
	v_pk_add_f32 v[58:59], v[100:101], 1.0 op_sel_hi:[1, 0]
	v_pk_fma_f32 v[36:37], v[58:59], v[50:51], v[104:105]
	v_pk_fma_f32 v[38:39], v[56:57], v[52:53], v[106:107]
	v_cvt_pk_bf16_f32 v36, v36, v37
	v_pk_mul_f32 v[50:51], v[42:43], v[0:1] op_sel_hi:[1, 0]
	v_cvt_pk_bf16_f32 v37, v38, v39
	global_store_dwordx2 v[54:55], v[36:37], off offset:512
	v_pk_mul_f32 v[52:53], v[40:41], v[0:1] op_sel_hi:[1, 0]
	v_pk_fma_f32 v[42:43], v[110:111], v[52:53], v[114:115]
	v_pk_fma_f32 v[40:41], v[108:109], v[50:51], v[112:113]
	v_cvt_pk_f16_f32 v37, v42, v43
	v_cvt_pk_f16_f32 v36, v40, v41
	global_store_dwordx2 v[48:49], v[36:37], off offset:1024
	v_pk_add_f32 v[50:51], v[118:119], 1.0 op_sel_hi:[1, 0]
	v_pk_add_f32 v[52:53], v[116:117], 1.0 op_sel_hi:[1, 0]
	v_pk_fma_f32 v[36:37], v[52:53], v[40:41], v[120:121]
	v_pk_fma_f32 v[38:39], v[50:51], v[42:43], v[122:123]
	v_cvt_pk_bf16_f32 v36, v36, v37
	s_nop 0
	v_cvt_pk_bf16_f32 v37, v38, v39
	global_store_dwordx2 v[54:55], v[36:37], off offset:1024
	s_nop 0
	v_pk_fma_f32 v[42:43], v[44:45], v[126:127], v[130:131]
	v_pk_fma_f32 v[40:41], v[46:47], v[124:125], v[128:129]
	v_cvt_pk_f16_f32 v37, v42, v43
	v_cvt_pk_f16_f32 v36, v40, v41
	global_store_dwordx2 v[48:49], v[36:37], off offset:1536
	v_pk_add_f32 v[44:45], v[134:135], 1.0 op_sel_hi:[1, 0]
	v_pk_add_f32 v[46:47], v[132:133], 1.0 op_sel_hi:[1, 0]
	v_pk_fma_f32 v[36:37], v[40:41], v[46:47], v[136:137]
	v_pk_fma_f32 v[38:39], v[42:43], v[44:45], v[138:139]
	v_cvt_pk_bf16_f32 v36, v36, v37
	s_nop 0
	v_cvt_pk_bf16_f32 v37, v38, v39
	global_store_dwordx2 v[54:55], v[36:37], off offset:1536
	s_cbranch_scc1 .LBB0_1271
